# shift-table job in the tail slot uses packed f32 FMA (two partial sums per table entry)
# speedup vs baseline: 1.0550x; 1.0029x over previous
; __device__ __forceinline__ void cb_item(const bf16_t* WT, int ldw, int K, int n0, const float* shift, float* out, int ostride, int lane) {
;     const bf16_t* wp = WT + (size_t)(n0 + lane) * ldw;
;     float a[5] = {0.f, 0.f, 0.f, 0.f, 0.f};
; #pragma unroll 4
;     for (int k8 = 0; k8 < K; k8 += 8) {
;         const u32x4 q = *(const u32x4*)(wp + k8);
;         float w[8];
; #pragma unroll
;         for (int e = 0; e < 4; ++e) { w[2 * e] = __uint_as_float(q[e] << 16); w[2 * e + 1] = __uint_as_float(q[e] & 0xffff0000u); }
; #pragma unroll
;         for (int b = 0; b < 5; ++b) { const float* sp = shift + (size_t)b * 9216 + k8;
; #pragma unroll
;             for (int e = 0; e < 8; ++e) a[b] += w[e] * sp[e]; }
;     }
; __device__ __forceinline__ void cb_tables(const Params& p) {
;     ...
;     for (int it = blockIdx.x + G * wave; it < 4 * 88 + 40 + 32; it += 8 * G) {
;         if (it < 352) { const int mi = it / 88, ch = it % 88, layer = mi >> 1, sub = mi & 1;
;             cb_item((const bf16_t*)(ws + WS_W1T + mi * SZ_W1T), D, D, ch * 64, MOD + (size_t)layer * 5 * 9216 + (sub ? 6 : 0) * 1024, (float*)(ws + WS_CB) + (size_t)mi * 5 * NFF1, NFF1, lane); }
.LBB0_1141:
	s_waitcnt vmcnt(0)
	s_barrier
	s_cmpk_lg_u32 s78, 0x100
	s_cbranch_scc1 .Ltr_done_b
	s_cmpk_lt_u32 s68, 0x80
	s_cbranch_scc1 .Ltr_done_b
	s_mov_b64 s[38:39], exec
	s_mov_b64 exec, -1
	v_readfirstlane_b32 s99, v176
	s_lshr_b32 s99, s99, 6
	s_sub_i32 s37, s68, 0x80
	s_cmp_lg_u32 s99, 0
	s_cbranch_scc1 .Ltr_w17_b
	s_cmpk_ge_u32 s37, 0x58
	s_cbranch_scc1 .Ltr_fin_b
	v_and_b32_e32 v16, 63, v176
	s_lshl_b32 s0, s37, 17
	s_add_u32 s0, s0, 0x2300000
	s_add_u32 s32, s76, s0
	s_addc_u32 s33, s77, 0
	s_add_u32 s34, s76, 0x33000
	s_addc_u32 s35, s77, 0
	v_lshlrev_b32_e32 v17, 11, v16
	v_mul_u32_u24_e32 v18, 0xa0, v16
	v_lshlrev_b32_e32 v19, 5, v16
	v_mov_b32_e32 v156, 0
	v_mov_b32_e32 v157, 0
	v_mov_b32_e32 v158, 0
	v_mov_b32_e32 v159, 0
	v_mov_b32_e32 v160, 0
	v_mov_b32_e32 v161, 0
	v_mov_b32_e32 v162, 0
	v_mov_b32_e32 v163, 0
	v_mov_b32_e32 v164, 0
	v_mov_b32_e32 v165, 0
	s_add_u32 s0, s34, 0x0
	s_addc_u32 s1, s35, 0
	global_load_dwordx4 v[28:31], v19, s[0:1]
	global_load_dwordx4 v[32:35], v19, s[0:1] offset:16
	s_add_u32 s0, s0, 0x9000
	s_addc_u32 s1, s1, 0
	global_load_dwordx4 v[36:39], v19, s[0:1]
	global_load_dwordx4 v[40:43], v19, s[0:1] offset:16
	s_add_u32 s0, s0, 0x9000
	s_addc_u32 s1, s1, 0
	global_load_dwordx4 v[44:47], v19, s[0:1]
	global_load_dwordx4 v[48:51], v19, s[0:1] offset:16
	s_add_u32 s0, s0, 0x9000
	s_addc_u32 s1, s1, 0
	global_load_dwordx4 v[52:55], v19, s[0:1]
	global_load_dwordx4 v[56:59], v19, s[0:1] offset:16
	s_add_u32 s0, s0, 0x9000
	s_addc_u32 s1, s1, 0
	global_load_dwordx4 v[140:143], v19, s[0:1]
	global_load_dwordx4 v[144:147], v19, s[0:1] offset:16
	s_waitcnt vmcnt(0)
	ds_write_b128 v18, v[28:31]
	ds_write_b128 v18, v[32:35] offset:16
	ds_write_b128 v18, v[36:39] offset:32
	ds_write_b128 v18, v[40:43] offset:48
	ds_write_b128 v18, v[44:47] offset:64
	ds_write_b128 v18, v[48:51] offset:80
	ds_write_b128 v18, v[52:55] offset:96
	ds_write_b128 v18, v[56:59] offset:112
	ds_write_b128 v18, v[140:143] offset:128
	ds_write_b128 v18, v[144:147] offset:144
	s_waitcnt lgkmcnt(0)
	v_add_u32_e32 v25, 0x0, v17
	v_mov_b32_e32 v26, 0
	global_load_dwordx4 v[28:31], v25, s[32:33]
	global_load_dwordx4 v[32:35], v25, s[32:33] offset:16
	global_load_dwordx4 v[36:39], v25, s[32:33] offset:32
	global_load_dwordx4 v[40:43], v25, s[32:33] offset:48
	global_load_dwordx4 v[44:47], v25, s[32:33] offset:64
	global_load_dwordx4 v[48:51], v25, s[32:33] offset:80
	global_load_dwordx4 v[52:55], v25, s[32:33] offset:96
	global_load_dwordx4 v[56:59], v25, s[32:33] offset:112
	ds_read_b128 v[60:63], v26
	ds_read_b128 v[64:67], v26 offset:16
	ds_read_b128 v[68:71], v26 offset:32
	ds_read_b128 v[72:75], v26 offset:48
	ds_read_b128 v[76:79], v26 offset:64
	ds_read_b128 v[80:83], v26 offset:80
	ds_read_b128 v[84:87], v26 offset:96
	ds_read_b128 v[88:91], v26 offset:112
	ds_read_b128 v[92:95], v26 offset:128
	ds_read_b128 v[96:99], v26 offset:144
	s_mov_b32 s100, 8
.Lcb_loop_b_0:
	ds_read_b128 v[100:103], v26 offset:160
	ds_read_b128 v[104:107], v26 offset:176
	ds_read_b128 v[108:111], v26 offset:192
	ds_read_b128 v[112:115], v26 offset:208
	ds_read_b128 v[116:119], v26 offset:224
	ds_read_b128 v[120:123], v26 offset:240
	ds_read_b128 v[124:127], v26 offset:256
	ds_read_b128 v[128:131], v26 offset:272
	ds_read_b128 v[132:135], v26 offset:288
	ds_read_b128 v[136:139], v26 offset:304
	s_waitcnt vmcnt(7)
	v_lshlrev_b32_e32 v148, 16, v28
	v_and_b32_e32 v149, 0xffff0000, v28
	v_lshlrev_b32_e32 v150, 16, v29
	v_and_b32_e32 v151, 0xffff0000, v29
	v_lshlrev_b32_e32 v152, 16, v30
	v_and_b32_e32 v153, 0xffff0000, v30
	v_lshlrev_b32_e32 v154, 16, v31
	v_and_b32_e32 v155, 0xffff0000, v31
	global_load_dwordx4 v[28:31], v25, s[32:33] offset:128
	s_waitcnt lgkmcnt(10)
	v_pk_fma_f32 v[156:157], v[148:149], v[60:61], v[156:157]
	v_pk_fma_f32 v[158:159], v[148:149], v[68:69], v[158:159]
	v_pk_fma_f32 v[160:161], v[148:149], v[76:77], v[160:161]
	v_pk_fma_f32 v[162:163], v[148:149], v[84:85], v[162:163]
	v_pk_fma_f32 v[164:165], v[148:149], v[92:93], v[164:165]
	v_pk_fma_f32 v[156:157], v[150:151], v[62:63], v[156:157]
	v_pk_fma_f32 v[158:159], v[150:151], v[70:71], v[158:159]
	v_pk_fma_f32 v[160:161], v[150:151], v[78:79], v[160:161]
	v_pk_fma_f32 v[162:163], v[150:151], v[86:87], v[162:163]
	v_pk_fma_f32 v[164:165], v[150:151], v[94:95], v[164:165]
	v_pk_fma_f32 v[156:157], v[152:153], v[64:65], v[156:157]
	v_pk_fma_f32 v[158:159], v[152:153], v[72:73], v[158:159]
	v_pk_fma_f32 v[160:161], v[152:153], v[80:81], v[160:161]
	v_pk_fma_f32 v[162:163], v[152:153], v[88:89], v[162:163]
	v_pk_fma_f32 v[164:165], v[152:153], v[96:97], v[164:165]
	v_pk_fma_f32 v[156:157], v[154:155], v[66:67], v[156:157]
	v_pk_fma_f32 v[158:159], v[154:155], v[74:75], v[158:159]
	v_pk_fma_f32 v[160:161], v[154:155], v[82:83], v[160:161]
	v_pk_fma_f32 v[162:163], v[154:155], v[90:91], v[162:163]
	v_pk_fma_f32 v[164:165], v[154:155], v[98:99], v[164:165]
	ds_read_b128 v[60:63], v26 offset:320
	ds_read_b128 v[64:67], v26 offset:336
	ds_read_b128 v[68:71], v26 offset:352
	ds_read_b128 v[72:75], v26 offset:368
	ds_read_b128 v[76:79], v26 offset:384
	ds_read_b128 v[80:83], v26 offset:400
	ds_read_b128 v[84:87], v26 offset:416
	ds_read_b128 v[88:91], v26 offset:432
	ds_read_b128 v[92:95], v26 offset:448
	ds_read_b128 v[96:99], v26 offset:464
	s_waitcnt vmcnt(7)
	v_lshlrev_b32_e32 v148, 16, v32
	v_and_b32_e32 v149, 0xffff0000, v32
	v_lshlrev_b32_e32 v150, 16, v33
	v_and_b32_e32 v151, 0xffff0000, v33
	v_lshlrev_b32_e32 v152, 16, v34
	v_and_b32_e32 v153, 0xffff0000, v34
	v_lshlrev_b32_e32 v154, 16, v35
	v_and_b32_e32 v155, 0xffff0000, v35
	global_load_dwordx4 v[32:35], v25, s[32:33] offset:144
	s_waitcnt lgkmcnt(10)
; __device__ __forceinline__ void cb_item(const bf16_t* WT, int ldw, int K, int n0, const float* shift, float* out, int ostride, int lane) {
;     ...
;     for (int k8 = 0; k8 < K; k8 += 8) {
;         const u32x4 q = *(const u32x4*)(wp + k8);
;         float w[8];
; #pragma unroll
;         for (int e = 0; e < 4; ++e) { w[2 * e] = __uint_as_float(q[e] << 16); w[2 * e + 1] = __uint_as_float(q[e] & 0xffff0000u); }
; #pragma unroll
;         for (int b = 0; b < 5; ++b) { const float* sp = shift + (size_t)b * 9216 + k8;
; #pragma unroll
;             for (int e = 0; e < 8; ++e) a[b] += w[e] * sp[e]; }
	v_pk_fma_f32 v[156:157], v[148:149], v[100:101], v[156:157]
	v_pk_fma_f32 v[158:159], v[148:149], v[108:109], v[158:159]
	v_pk_fma_f32 v[160:161], v[148:149], v[116:117], v[160:161]
	v_pk_fma_f32 v[162:163], v[148:149], v[124:125], v[162:163]
	v_pk_fma_f32 v[164:165], v[148:149], v[132:133], v[164:165]
	v_pk_fma_f32 v[156:157], v[150:151], v[102:103], v[156:157]
	v_pk_fma_f32 v[158:159], v[150:151], v[110:111], v[158:159]
	v_pk_fma_f32 v[160:161], v[150:151], v[118:119], v[160:161]
	v_pk_fma_f32 v[162:163], v[150:151], v[126:127], v[162:163]
	v_pk_fma_f32 v[164:165], v[150:151], v[134:135], v[164:165]
	v_pk_fma_f32 v[156:157], v[152:153], v[104:105], v[156:157]
	v_pk_fma_f32 v[158:159], v[152:153], v[112:113], v[158:159]
	v_pk_fma_f32 v[160:161], v[152:153], v[120:121], v[160:161]
	v_pk_fma_f32 v[162:163], v[152:153], v[128:129], v[162:163]
	v_pk_fma_f32 v[164:165], v[152:153], v[136:137], v[164:165]
	v_pk_fma_f32 v[156:157], v[154:155], v[106:107], v[156:157]
	v_pk_fma_f32 v[158:159], v[154:155], v[114:115], v[158:159]
	v_pk_fma_f32 v[160:161], v[154:155], v[122:123], v[160:161]
	v_pk_fma_f32 v[162:163], v[154:155], v[130:131], v[162:163]
	v_pk_fma_f32 v[164:165], v[154:155], v[138:139], v[164:165]
	ds_read_b128 v[100:103], v26 offset:480
	ds_read_b128 v[104:107], v26 offset:496
	ds_read_b128 v[108:111], v26 offset:512
	ds_read_b128 v[112:115], v26 offset:528
	ds_read_b128 v[116:119], v26 offset:544
	ds_read_b128 v[120:123], v26 offset:560
	ds_read_b128 v[124:127], v26 offset:576
	ds_read_b128 v[128:131], v26 offset:592
	ds_read_b128 v[132:135], v26 offset:608
	ds_read_b128 v[136:139], v26 offset:624
	s_waitcnt vmcnt(7)
	v_lshlrev_b32_e32 v148, 16, v36
	v_and_b32_e32 v149, 0xffff0000, v36
	v_lshlrev_b32_e32 v150, 16, v37
	v_and_b32_e32 v151, 0xffff0000, v37
	v_lshlrev_b32_e32 v152, 16, v38
	v_and_b32_e32 v153, 0xffff0000, v38
	v_lshlrev_b32_e32 v154, 16, v39
	v_and_b32_e32 v155, 0xffff0000, v39
	global_load_dwordx4 v[36:39], v25, s[32:33] offset:160
	s_waitcnt lgkmcnt(10)
	v_pk_fma_f32 v[156:157], v[148:149], v[60:61], v[156:157]
	v_pk_fma_f32 v[158:159], v[148:149], v[68:69], v[158:159]
	v_pk_fma_f32 v[160:161], v[148:149], v[76:77], v[160:161]
	v_pk_fma_f32 v[162:163], v[148:149], v[84:85], v[162:163]
	v_pk_fma_f32 v[164:165], v[148:149], v[92:93], v[164:165]
	v_pk_fma_f32 v[156:157], v[150:151], v[62:63], v[156:157]
	v_pk_fma_f32 v[158:159], v[150:151], v[70:71], v[158:159]
	v_pk_fma_f32 v[160:161], v[150:151], v[78:79], v[160:161]
	v_pk_fma_f32 v[162:163], v[150:151], v[86:87], v[162:163]
	v_pk_fma_f32 v[164:165], v[150:151], v[94:95], v[164:165]
	v_pk_fma_f32 v[156:157], v[152:153], v[64:65], v[156:157]
	v_pk_fma_f32 v[158:159], v[152:153], v[72:73], v[158:159]
	v_pk_fma_f32 v[160:161], v[152:153], v[80:81], v[160:161]
	v_pk_fma_f32 v[162:163], v[152:153], v[88:89], v[162:163]
	v_pk_fma_f32 v[164:165], v[152:153], v[96:97], v[164:165]
	v_pk_fma_f32 v[156:157], v[154:155], v[66:67], v[156:157]
	v_pk_fma_f32 v[158:159], v[154:155], v[74:75], v[158:159]
	v_pk_fma_f32 v[160:161], v[154:155], v[82:83], v[160:161]
	v_pk_fma_f32 v[162:163], v[154:155], v[90:91], v[162:163]
	v_pk_fma_f32 v[164:165], v[154:155], v[98:99], v[164:165]
	ds_read_b128 v[60:63], v26 offset:640
	ds_read_b128 v[64:67], v26 offset:656
	ds_read_b128 v[68:71], v26 offset:672
	ds_read_b128 v[72:75], v26 offset:688
	ds_read_b128 v[76:79], v26 offset:704
	ds_read_b128 v[80:83], v26 offset:720
	ds_read_b128 v[84:87], v26 offset:736
	ds_read_b128 v[88:91], v26 offset:752
	ds_read_b128 v[92:95], v26 offset:768
	ds_read_b128 v[96:99], v26 offset:784
	s_waitcnt vmcnt(7)
	v_lshlrev_b32_e32 v148, 16, v40
	v_and_b32_e32 v149, 0xffff0000, v40
	v_lshlrev_b32_e32 v150, 16, v41
	v_and_b32_e32 v151, 0xffff0000, v41
	v_lshlrev_b32_e32 v152, 16, v42
	v_and_b32_e32 v153, 0xffff0000, v42
	v_lshlrev_b32_e32 v154, 16, v43
	v_and_b32_e32 v155, 0xffff0000, v43
	global_load_dwordx4 v[40:43], v25, s[32:33] offset:176
	s_waitcnt lgkmcnt(10)
	v_pk_fma_f32 v[156:157], v[148:149], v[100:101], v[156:157]
	v_pk_fma_f32 v[158:159], v[148:149], v[108:109], v[158:159]
	v_pk_fma_f32 v[160:161], v[148:149], v[116:117], v[160:161]
	v_pk_fma_f32 v[162:163], v[148:149], v[124:125], v[162:163]
	v_pk_fma_f32 v[164:165], v[148:149], v[132:133], v[164:165]
	v_pk_fma_f32 v[156:157], v[150:151], v[102:103], v[156:157]
	v_pk_fma_f32 v[158:159], v[150:151], v[110:111], v[158:159]
	v_pk_fma_f32 v[160:161], v[150:151], v[118:119], v[160:161]
	v_pk_fma_f32 v[162:163], v[150:151], v[126:127], v[162:163]
	v_pk_fma_f32 v[164:165], v[150:151], v[134:135], v[164:165]
	v_pk_fma_f32 v[156:157], v[152:153], v[104:105], v[156:157]
	v_pk_fma_f32 v[158:159], v[152:153], v[112:113], v[158:159]
	v_pk_fma_f32 v[160:161], v[152:153], v[120:121], v[160:161]
	v_pk_fma_f32 v[162:163], v[152:153], v[128:129], v[162:163]
	v_pk_fma_f32 v[164:165], v[152:153], v[136:137], v[164:165]
	v_pk_fma_f32 v[156:157], v[154:155], v[106:107], v[156:157]
	v_pk_fma_f32 v[158:159], v[154:155], v[114:115], v[158:159]
	v_pk_fma_f32 v[160:161], v[154:155], v[122:123], v[160:161]
	v_pk_fma_f32 v[162:163], v[154:155], v[130:131], v[162:163]
	v_pk_fma_f32 v[164:165], v[154:155], v[138:139], v[164:165]
	ds_read_b128 v[100:103], v26 offset:800
	ds_read_b128 v[104:107], v26 offset:816
	ds_read_b128 v[108:111], v26 offset:832
	ds_read_b128 v[112:115], v26 offset:848
	ds_read_b128 v[116:119], v26 offset:864
	ds_read_b128 v[120:123], v26 offset:880
	ds_read_b128 v[124:127], v26 offset:896
	ds_read_b128 v[128:131], v26 offset:912
	ds_read_b128 v[132:135], v26 offset:928
	ds_read_b128 v[136:139], v26 offset:944
	s_waitcnt vmcnt(7)
; __device__ __forceinline__ void cb_item(const bf16_t* WT, int ldw, int K, int n0, const float* shift, float* out, int ostride, int lane) {
;     ...
;     for (int k8 = 0; k8 < K; k8 += 8) {
;         const u32x4 q = *(const u32x4*)(wp + k8);
;         float w[8];
; #pragma unroll
;         for (int e = 0; e < 4; ++e) { w[2 * e] = __uint_as_float(q[e] << 16); w[2 * e + 1] = __uint_as_float(q[e] & 0xffff0000u); }
; #pragma unroll
;         for (int b = 0; b < 5; ++b) { const float* sp = shift + (size_t)b * 9216 + k8;
; #pragma unroll
;             for (int e = 0; e < 8; ++e) a[b] += w[e] * sp[e]; }
	v_lshlrev_b32_e32 v148, 16, v44
	v_and_b32_e32 v149, 0xffff0000, v44
	v_lshlrev_b32_e32 v150, 16, v45
	v_and_b32_e32 v151, 0xffff0000, v45
	v_lshlrev_b32_e32 v152, 16, v46
	v_and_b32_e32 v153, 0xffff0000, v46
	v_lshlrev_b32_e32 v154, 16, v47
	v_and_b32_e32 v155, 0xffff0000, v47
	global_load_dwordx4 v[44:47], v25, s[32:33] offset:192
	s_waitcnt lgkmcnt(10)
	v_pk_fma_f32 v[156:157], v[148:149], v[60:61], v[156:157]
	v_pk_fma_f32 v[158:159], v[148:149], v[68:69], v[158:159]
	v_pk_fma_f32 v[160:161], v[148:149], v[76:77], v[160:161]
	v_pk_fma_f32 v[162:163], v[148:149], v[84:85], v[162:163]
	v_pk_fma_f32 v[164:165], v[148:149], v[92:93], v[164:165]
	v_pk_fma_f32 v[156:157], v[150:151], v[62:63], v[156:157]
	v_pk_fma_f32 v[158:159], v[150:151], v[70:71], v[158:159]
	v_pk_fma_f32 v[160:161], v[150:151], v[78:79], v[160:161]
	v_pk_fma_f32 v[162:163], v[150:151], v[86:87], v[162:163]
	v_pk_fma_f32 v[164:165], v[150:151], v[94:95], v[164:165]
	v_pk_fma_f32 v[156:157], v[152:153], v[64:65], v[156:157]
	v_pk_fma_f32 v[158:159], v[152:153], v[72:73], v[158:159]
	v_pk_fma_f32 v[160:161], v[152:153], v[80:81], v[160:161]
	v_pk_fma_f32 v[162:163], v[152:153], v[88:89], v[162:163]
	v_pk_fma_f32 v[164:165], v[152:153], v[96:97], v[164:165]
	v_pk_fma_f32 v[156:157], v[154:155], v[66:67], v[156:157]
	v_pk_fma_f32 v[158:159], v[154:155], v[74:75], v[158:159]
	v_pk_fma_f32 v[160:161], v[154:155], v[82:83], v[160:161]
	v_pk_fma_f32 v[162:163], v[154:155], v[90:91], v[162:163]
	v_pk_fma_f32 v[164:165], v[154:155], v[98:99], v[164:165]
	ds_read_b128 v[60:63], v26 offset:960
	ds_read_b128 v[64:67], v26 offset:976
	ds_read_b128 v[68:71], v26 offset:992
	ds_read_b128 v[72:75], v26 offset:1008
	ds_read_b128 v[76:79], v26 offset:1024
	ds_read_b128 v[80:83], v26 offset:1040
	ds_read_b128 v[84:87], v26 offset:1056
	ds_read_b128 v[88:91], v26 offset:1072
	ds_read_b128 v[92:95], v26 offset:1088
	ds_read_b128 v[96:99], v26 offset:1104
	s_waitcnt vmcnt(7)
	v_lshlrev_b32_e32 v148, 16, v48
	v_and_b32_e32 v149, 0xffff0000, v48
	v_lshlrev_b32_e32 v150, 16, v49
	v_and_b32_e32 v151, 0xffff0000, v49
	v_lshlrev_b32_e32 v152, 16, v50
	v_and_b32_e32 v153, 0xffff0000, v50
	v_lshlrev_b32_e32 v154, 16, v51
	v_and_b32_e32 v155, 0xffff0000, v51
	global_load_dwordx4 v[48:51], v25, s[32:33] offset:208
	s_waitcnt lgkmcnt(10)
	v_pk_fma_f32 v[156:157], v[148:149], v[100:101], v[156:157]
	v_pk_fma_f32 v[158:159], v[148:149], v[108:109], v[158:159]
	v_pk_fma_f32 v[160:161], v[148:149], v[116:117], v[160:161]
	v_pk_fma_f32 v[162:163], v[148:149], v[124:125], v[162:163]
	v_pk_fma_f32 v[164:165], v[148:149], v[132:133], v[164:165]
	v_pk_fma_f32 v[156:157], v[150:151], v[102:103], v[156:157]
	v_pk_fma_f32 v[158:159], v[150:151], v[110:111], v[158:159]
	v_pk_fma_f32 v[160:161], v[150:151], v[118:119], v[160:161]
	v_pk_fma_f32 v[162:163], v[150:151], v[126:127], v[162:163]
	v_pk_fma_f32 v[164:165], v[150:151], v[134:135], v[164:165]
	v_pk_fma_f32 v[156:157], v[152:153], v[104:105], v[156:157]
	v_pk_fma_f32 v[158:159], v[152:153], v[112:113], v[158:159]
	v_pk_fma_f32 v[160:161], v[152:153], v[120:121], v[160:161]
	v_pk_fma_f32 v[162:163], v[152:153], v[128:129], v[162:163]
	v_pk_fma_f32 v[164:165], v[152:153], v[136:137], v[164:165]
	v_pk_fma_f32 v[156:157], v[154:155], v[106:107], v[156:157]
	v_pk_fma_f32 v[158:159], v[154:155], v[114:115], v[158:159]
	v_pk_fma_f32 v[160:161], v[154:155], v[122:123], v[160:161]
	v_pk_fma_f32 v[162:163], v[154:155], v[130:131], v[162:163]
	v_pk_fma_f32 v[164:165], v[154:155], v[138:139], v[164:165]
	ds_read_b128 v[100:103], v26 offset:1120
	ds_read_b128 v[104:107], v26 offset:1136
	ds_read_b128 v[108:111], v26 offset:1152
	ds_read_b128 v[112:115], v26 offset:1168
	ds_read_b128 v[116:119], v26 offset:1184
	ds_read_b128 v[120:123], v26 offset:1200
	ds_read_b128 v[124:127], v26 offset:1216
	ds_read_b128 v[128:131], v26 offset:1232
	ds_read_b128 v[132:135], v26 offset:1248
	ds_read_b128 v[136:139], v26 offset:1264
	s_waitcnt vmcnt(7)
	v_lshlrev_b32_e32 v148, 16, v52
	v_and_b32_e32 v149, 0xffff0000, v52
	v_lshlrev_b32_e32 v150, 16, v53
	v_and_b32_e32 v151, 0xffff0000, v53
	v_lshlrev_b32_e32 v152, 16, v54
	v_and_b32_e32 v153, 0xffff0000, v54
	v_lshlrev_b32_e32 v154, 16, v55
	v_and_b32_e32 v155, 0xffff0000, v55
	global_load_dwordx4 v[52:55], v25, s[32:33] offset:224
	s_waitcnt lgkmcnt(10)
	v_pk_fma_f32 v[156:157], v[148:149], v[60:61], v[156:157]
	v_pk_fma_f32 v[158:159], v[148:149], v[68:69], v[158:159]
	v_pk_fma_f32 v[160:161], v[148:149], v[76:77], v[160:161]
	v_pk_fma_f32 v[162:163], v[148:149], v[84:85], v[162:163]
	v_pk_fma_f32 v[164:165], v[148:149], v[92:93], v[164:165]
	v_pk_fma_f32 v[156:157], v[150:151], v[62:63], v[156:157]
	v_pk_fma_f32 v[158:159], v[150:151], v[70:71], v[158:159]
	v_pk_fma_f32 v[160:161], v[150:151], v[78:79], v[160:161]
	v_pk_fma_f32 v[162:163], v[150:151], v[86:87], v[162:163]
	v_pk_fma_f32 v[164:165], v[150:151], v[94:95], v[164:165]
	v_pk_fma_f32 v[156:157], v[152:153], v[64:65], v[156:157]
	v_pk_fma_f32 v[158:159], v[152:153], v[72:73], v[158:159]
	v_pk_fma_f32 v[160:161], v[152:153], v[80:81], v[160:161]
	v_pk_fma_f32 v[162:163], v[152:153], v[88:89], v[162:163]
	v_pk_fma_f32 v[164:165], v[152:153], v[96:97], v[164:165]
	v_pk_fma_f32 v[156:157], v[154:155], v[66:67], v[156:157]
	v_pk_fma_f32 v[158:159], v[154:155], v[74:75], v[158:159]
	v_pk_fma_f32 v[160:161], v[154:155], v[82:83], v[160:161]
	v_pk_fma_f32 v[162:163], v[154:155], v[90:91], v[162:163]
	v_pk_fma_f32 v[164:165], v[154:155], v[98:99], v[164:165]
	ds_read_b128 v[60:63], v26 offset:1280
	ds_read_b128 v[64:67], v26 offset:1296
	ds_read_b128 v[68:71], v26 offset:1312
	ds_read_b128 v[72:75], v26 offset:1328
	ds_read_b128 v[76:79], v26 offset:1344
	ds_read_b128 v[80:83], v26 offset:1360
	ds_read_b128 v[84:87], v26 offset:1376
	ds_read_b128 v[88:91], v26 offset:1392
	ds_read_b128 v[92:95], v26 offset:1408
	ds_read_b128 v[96:99], v26 offset:1424
	s_waitcnt vmcnt(7)
; __device__ __forceinline__ void cb_item(const bf16_t* WT, int ldw, int K, int n0, const float* shift, float* out, int ostride, int lane) {
;     ...
;     for (int k8 = 0; k8 < K; k8 += 8) {
;         const u32x4 q = *(const u32x4*)(wp + k8);
;         float w[8];
; #pragma unroll
;         for (int e = 0; e < 4; ++e) { w[2 * e] = __uint_as_float(q[e] << 16); w[2 * e + 1] = __uint_as_float(q[e] & 0xffff0000u); }
; #pragma unroll
;         for (int b = 0; b < 5; ++b) { const float* sp = shift + (size_t)b * 9216 + k8;
; #pragma unroll
;             for (int e = 0; e < 8; ++e) a[b] += w[e] * sp[e]; }
	v_lshlrev_b32_e32 v148, 16, v56
	v_and_b32_e32 v149, 0xffff0000, v56
	v_lshlrev_b32_e32 v150, 16, v57
	v_and_b32_e32 v151, 0xffff0000, v57
	v_lshlrev_b32_e32 v152, 16, v58
	v_and_b32_e32 v153, 0xffff0000, v58
	v_lshlrev_b32_e32 v154, 16, v59
	v_and_b32_e32 v155, 0xffff0000, v59
	global_load_dwordx4 v[56:59], v25, s[32:33] offset:240
	s_waitcnt lgkmcnt(10)
	v_pk_fma_f32 v[156:157], v[148:149], v[100:101], v[156:157]
	v_pk_fma_f32 v[158:159], v[148:149], v[108:109], v[158:159]
	v_pk_fma_f32 v[160:161], v[148:149], v[116:117], v[160:161]
	v_pk_fma_f32 v[162:163], v[148:149], v[124:125], v[162:163]
	v_pk_fma_f32 v[164:165], v[148:149], v[132:133], v[164:165]
	v_pk_fma_f32 v[156:157], v[150:151], v[102:103], v[156:157]
	v_pk_fma_f32 v[158:159], v[150:151], v[110:111], v[158:159]
	v_pk_fma_f32 v[160:161], v[150:151], v[118:119], v[160:161]
	v_pk_fma_f32 v[162:163], v[150:151], v[126:127], v[162:163]
	v_pk_fma_f32 v[164:165], v[150:151], v[134:135], v[164:165]
	v_pk_fma_f32 v[156:157], v[152:153], v[104:105], v[156:157]
	v_pk_fma_f32 v[158:159], v[152:153], v[112:113], v[158:159]
	v_pk_fma_f32 v[160:161], v[152:153], v[120:121], v[160:161]
	v_pk_fma_f32 v[162:163], v[152:153], v[128:129], v[162:163]
	v_pk_fma_f32 v[164:165], v[152:153], v[136:137], v[164:165]
	v_pk_fma_f32 v[156:157], v[154:155], v[106:107], v[156:157]
	v_pk_fma_f32 v[158:159], v[154:155], v[114:115], v[158:159]
	v_pk_fma_f32 v[160:161], v[154:155], v[122:123], v[160:161]
	v_pk_fma_f32 v[162:163], v[154:155], v[130:131], v[162:163]
	v_pk_fma_f32 v[164:165], v[154:155], v[138:139], v[164:165]
	v_add_u32_e32 v25, 0x80, v25
	v_add_u32_e32 v26, 0x500, v26
	s_add_i32 s100, s100, -1
	s_cmp_lg_u32 s100, 0
	s_cbranch_scc1 .Lcb_loop_b_0
	s_waitcnt vmcnt(0) lgkmcnt(0)
	s_add_u32 s0, s34, 0x800
	s_addc_u32 s1, s35, 0
	global_load_dwordx4 v[28:31], v19, s[0:1]
	global_load_dwordx4 v[32:35], v19, s[0:1] offset:16
	s_add_u32 s0, s0, 0x9000
	s_addc_u32 s1, s1, 0
	global_load_dwordx4 v[36:39], v19, s[0:1]
	global_load_dwordx4 v[40:43], v19, s[0:1] offset:16
	s_add_u32 s0, s0, 0x9000
	s_addc_u32 s1, s1, 0
	global_load_dwordx4 v[44:47], v19, s[0:1]
	global_load_dwordx4 v[48:51], v19, s[0:1] offset:16
	s_add_u32 s0, s0, 0x9000
	s_addc_u32 s1, s1, 0
	global_load_dwordx4 v[52:55], v19, s[0:1]
	global_load_dwordx4 v[56:59], v19, s[0:1] offset:16
	s_add_u32 s0, s0, 0x9000
	s_addc_u32 s1, s1, 0
	global_load_dwordx4 v[140:143], v19, s[0:1]
	global_load_dwordx4 v[144:147], v19, s[0:1] offset:16
	s_waitcnt vmcnt(0)
	ds_write_b128 v18, v[28:31]
	ds_write_b128 v18, v[32:35] offset:16
	ds_write_b128 v18, v[36:39] offset:32
	ds_write_b128 v18, v[40:43] offset:48
	ds_write_b128 v18, v[44:47] offset:64
	ds_write_b128 v18, v[48:51] offset:80
	ds_write_b128 v18, v[52:55] offset:96
	ds_write_b128 v18, v[56:59] offset:112
	ds_write_b128 v18, v[140:143] offset:128
	ds_write_b128 v18, v[144:147] offset:144
	s_waitcnt lgkmcnt(0)
	v_add_u32_e32 v25, 0x400, v17
	v_mov_b32_e32 v26, 0
	global_load_dwordx4 v[28:31], v25, s[32:33]
	global_load_dwordx4 v[32:35], v25, s[32:33] offset:16
	global_load_dwordx4 v[36:39], v25, s[32:33] offset:32
	global_load_dwordx4 v[40:43], v25, s[32:33] offset:48
	global_load_dwordx4 v[44:47], v25, s[32:33] offset:64
	global_load_dwordx4 v[48:51], v25, s[32:33] offset:80
	global_load_dwordx4 v[52:55], v25, s[32:33] offset:96
	global_load_dwordx4 v[56:59], v25, s[32:33] offset:112
	ds_read_b128 v[60:63], v26
	ds_read_b128 v[64:67], v26 offset:16
	ds_read_b128 v[68:71], v26 offset:32
	ds_read_b128 v[72:75], v26 offset:48
	ds_read_b128 v[76:79], v26 offset:64
	ds_read_b128 v[80:83], v26 offset:80
	ds_read_b128 v[84:87], v26 offset:96
	ds_read_b128 v[88:91], v26 offset:112
	ds_read_b128 v[92:95], v26 offset:128
	ds_read_b128 v[96:99], v26 offset:144
	s_mov_b32 s100, 8
.Lcb_loop_b_1:
	ds_read_b128 v[100:103], v26 offset:160
	ds_read_b128 v[104:107], v26 offset:176
	ds_read_b128 v[108:111], v26 offset:192
	ds_read_b128 v[112:115], v26 offset:208
	ds_read_b128 v[116:119], v26 offset:224
	ds_read_b128 v[120:123], v26 offset:240
	ds_read_b128 v[124:127], v26 offset:256
	ds_read_b128 v[128:131], v26 offset:272
	ds_read_b128 v[132:135], v26 offset:288
	ds_read_b128 v[136:139], v26 offset:304
	s_waitcnt vmcnt(7)
	v_lshlrev_b32_e32 v148, 16, v28
	v_and_b32_e32 v149, 0xffff0000, v28
	v_lshlrev_b32_e32 v150, 16, v29
	v_and_b32_e32 v151, 0xffff0000, v29
	v_lshlrev_b32_e32 v152, 16, v30
	v_and_b32_e32 v153, 0xffff0000, v30
	v_lshlrev_b32_e32 v154, 16, v31
	v_and_b32_e32 v155, 0xffff0000, v31
	global_load_dwordx4 v[28:31], v25, s[32:33] offset:128
	s_waitcnt lgkmcnt(10)
	v_pk_fma_f32 v[156:157], v[148:149], v[60:61], v[156:157]
	v_pk_fma_f32 v[158:159], v[148:149], v[68:69], v[158:159]
	v_pk_fma_f32 v[160:161], v[148:149], v[76:77], v[160:161]
	v_pk_fma_f32 v[162:163], v[148:149], v[84:85], v[162:163]
	v_pk_fma_f32 v[164:165], v[148:149], v[92:93], v[164:165]
	v_pk_fma_f32 v[156:157], v[150:151], v[62:63], v[156:157]
	v_pk_fma_f32 v[158:159], v[150:151], v[70:71], v[158:159]
	v_pk_fma_f32 v[160:161], v[150:151], v[78:79], v[160:161]
	v_pk_fma_f32 v[162:163], v[150:151], v[86:87], v[162:163]
	v_pk_fma_f32 v[164:165], v[150:151], v[94:95], v[164:165]
	v_pk_fma_f32 v[156:157], v[152:153], v[64:65], v[156:157]
	v_pk_fma_f32 v[158:159], v[152:153], v[72:73], v[158:159]
	v_pk_fma_f32 v[160:161], v[152:153], v[80:81], v[160:161]
	v_pk_fma_f32 v[162:163], v[152:153], v[88:89], v[162:163]
	v_pk_fma_f32 v[164:165], v[152:153], v[96:97], v[164:165]
	v_pk_fma_f32 v[156:157], v[154:155], v[66:67], v[156:157]
	v_pk_fma_f32 v[158:159], v[154:155], v[74:75], v[158:159]
	v_pk_fma_f32 v[160:161], v[154:155], v[82:83], v[160:161]
	v_pk_fma_f32 v[162:163], v[154:155], v[90:91], v[162:163]
	v_pk_fma_f32 v[164:165], v[154:155], v[98:99], v[164:165]
	ds_read_b128 v[60:63], v26 offset:320
	ds_read_b128 v[64:67], v26 offset:336
	ds_read_b128 v[68:71], v26 offset:352
	ds_read_b128 v[72:75], v26 offset:368
	ds_read_b128 v[76:79], v26 offset:384
	ds_read_b128 v[80:83], v26 offset:400
	ds_read_b128 v[84:87], v26 offset:416
	ds_read_b128 v[88:91], v26 offset:432
	ds_read_b128 v[92:95], v26 offset:448
	ds_read_b128 v[96:99], v26 offset:464
	s_waitcnt vmcnt(7)
; __device__ __forceinline__ void cb_item(const bf16_t* WT, int ldw, int K, int n0, const float* shift, float* out, int ostride, int lane) {
;     ...
;     for (int k8 = 0; k8 < K; k8 += 8) {
;         const u32x4 q = *(const u32x4*)(wp + k8);
;         float w[8];
; #pragma unroll
;         for (int e = 0; e < 4; ++e) { w[2 * e] = __uint_as_float(q[e] << 16); w[2 * e + 1] = __uint_as_float(q[e] & 0xffff0000u); }
; #pragma unroll
;         for (int b = 0; b < 5; ++b) { const float* sp = shift + (size_t)b * 9216 + k8;
; #pragma unroll
;             for (int e = 0; e < 8; ++e) a[b] += w[e] * sp[e]; }
	v_lshlrev_b32_e32 v148, 16, v32
	v_and_b32_e32 v149, 0xffff0000, v32
	v_lshlrev_b32_e32 v150, 16, v33
	v_and_b32_e32 v151, 0xffff0000, v33
	v_lshlrev_b32_e32 v152, 16, v34
	v_and_b32_e32 v153, 0xffff0000, v34
	v_lshlrev_b32_e32 v154, 16, v35
	v_and_b32_e32 v155, 0xffff0000, v35
	global_load_dwordx4 v[32:35], v25, s[32:33] offset:144
	s_waitcnt lgkmcnt(10)
	v_pk_fma_f32 v[156:157], v[148:149], v[100:101], v[156:157]
	v_pk_fma_f32 v[158:159], v[148:149], v[108:109], v[158:159]
	v_pk_fma_f32 v[160:161], v[148:149], v[116:117], v[160:161]
	v_pk_fma_f32 v[162:163], v[148:149], v[124:125], v[162:163]
	v_pk_fma_f32 v[164:165], v[148:149], v[132:133], v[164:165]
	v_pk_fma_f32 v[156:157], v[150:151], v[102:103], v[156:157]
	v_pk_fma_f32 v[158:159], v[150:151], v[110:111], v[158:159]
	v_pk_fma_f32 v[160:161], v[150:151], v[118:119], v[160:161]
	v_pk_fma_f32 v[162:163], v[150:151], v[126:127], v[162:163]
	v_pk_fma_f32 v[164:165], v[150:151], v[134:135], v[164:165]
	v_pk_fma_f32 v[156:157], v[152:153], v[104:105], v[156:157]
	v_pk_fma_f32 v[158:159], v[152:153], v[112:113], v[158:159]
	v_pk_fma_f32 v[160:161], v[152:153], v[120:121], v[160:161]
	v_pk_fma_f32 v[162:163], v[152:153], v[128:129], v[162:163]
	v_pk_fma_f32 v[164:165], v[152:153], v[136:137], v[164:165]
	v_pk_fma_f32 v[156:157], v[154:155], v[106:107], v[156:157]
	v_pk_fma_f32 v[158:159], v[154:155], v[114:115], v[158:159]
	v_pk_fma_f32 v[160:161], v[154:155], v[122:123], v[160:161]
	v_pk_fma_f32 v[162:163], v[154:155], v[130:131], v[162:163]
	v_pk_fma_f32 v[164:165], v[154:155], v[138:139], v[164:165]
	ds_read_b128 v[100:103], v26 offset:480
	ds_read_b128 v[104:107], v26 offset:496
	ds_read_b128 v[108:111], v26 offset:512
	ds_read_b128 v[112:115], v26 offset:528
	ds_read_b128 v[116:119], v26 offset:544
	ds_read_b128 v[120:123], v26 offset:560
	ds_read_b128 v[124:127], v26 offset:576
	ds_read_b128 v[128:131], v26 offset:592
	ds_read_b128 v[132:135], v26 offset:608
	ds_read_b128 v[136:139], v26 offset:624
	s_waitcnt vmcnt(7)
	v_lshlrev_b32_e32 v148, 16, v36
	v_and_b32_e32 v149, 0xffff0000, v36
	v_lshlrev_b32_e32 v150, 16, v37
	v_and_b32_e32 v151, 0xffff0000, v37
	v_lshlrev_b32_e32 v152, 16, v38
	v_and_b32_e32 v153, 0xffff0000, v38
	v_lshlrev_b32_e32 v154, 16, v39
	v_and_b32_e32 v155, 0xffff0000, v39
	global_load_dwordx4 v[36:39], v25, s[32:33] offset:160
	s_waitcnt lgkmcnt(10)
	v_pk_fma_f32 v[156:157], v[148:149], v[60:61], v[156:157]
	v_pk_fma_f32 v[158:159], v[148:149], v[68:69], v[158:159]
	v_pk_fma_f32 v[160:161], v[148:149], v[76:77], v[160:161]
	v_pk_fma_f32 v[162:163], v[148:149], v[84:85], v[162:163]
	v_pk_fma_f32 v[164:165], v[148:149], v[92:93], v[164:165]
	v_pk_fma_f32 v[156:157], v[150:151], v[62:63], v[156:157]
	v_pk_fma_f32 v[158:159], v[150:151], v[70:71], v[158:159]
	v_pk_fma_f32 v[160:161], v[150:151], v[78:79], v[160:161]
	v_pk_fma_f32 v[162:163], v[150:151], v[86:87], v[162:163]
	v_pk_fma_f32 v[164:165], v[150:151], v[94:95], v[164:165]
	v_pk_fma_f32 v[156:157], v[152:153], v[64:65], v[156:157]
	v_pk_fma_f32 v[158:159], v[152:153], v[72:73], v[158:159]
	v_pk_fma_f32 v[160:161], v[152:153], v[80:81], v[160:161]
	v_pk_fma_f32 v[162:163], v[152:153], v[88:89], v[162:163]
	v_pk_fma_f32 v[164:165], v[152:153], v[96:97], v[164:165]
	v_pk_fma_f32 v[156:157], v[154:155], v[66:67], v[156:157]
	v_pk_fma_f32 v[158:159], v[154:155], v[74:75], v[158:159]
	v_pk_fma_f32 v[160:161], v[154:155], v[82:83], v[160:161]
	v_pk_fma_f32 v[162:163], v[154:155], v[90:91], v[162:163]
	v_pk_fma_f32 v[164:165], v[154:155], v[98:99], v[164:165]
	ds_read_b128 v[60:63], v26 offset:640
	ds_read_b128 v[64:67], v26 offset:656
	ds_read_b128 v[68:71], v26 offset:672
	ds_read_b128 v[72:75], v26 offset:688
	ds_read_b128 v[76:79], v26 offset:704
	ds_read_b128 v[80:83], v26 offset:720
	ds_read_b128 v[84:87], v26 offset:736
	ds_read_b128 v[88:91], v26 offset:752
	ds_read_b128 v[92:95], v26 offset:768
	ds_read_b128 v[96:99], v26 offset:784
	s_waitcnt vmcnt(7)
	v_lshlrev_b32_e32 v148, 16, v40
	v_and_b32_e32 v149, 0xffff0000, v40
	v_lshlrev_b32_e32 v150, 16, v41
	v_and_b32_e32 v151, 0xffff0000, v41
	v_lshlrev_b32_e32 v152, 16, v42
	v_and_b32_e32 v153, 0xffff0000, v42
	v_lshlrev_b32_e32 v154, 16, v43
	v_and_b32_e32 v155, 0xffff0000, v43
	global_load_dwordx4 v[40:43], v25, s[32:33] offset:176
	s_waitcnt lgkmcnt(10)
	v_pk_fma_f32 v[156:157], v[148:149], v[100:101], v[156:157]
	v_pk_fma_f32 v[158:159], v[148:149], v[108:109], v[158:159]
	v_pk_fma_f32 v[160:161], v[148:149], v[116:117], v[160:161]
	v_pk_fma_f32 v[162:163], v[148:149], v[124:125], v[162:163]
	v_pk_fma_f32 v[164:165], v[148:149], v[132:133], v[164:165]
	v_pk_fma_f32 v[156:157], v[150:151], v[102:103], v[156:157]
	v_pk_fma_f32 v[158:159], v[150:151], v[110:111], v[158:159]
	v_pk_fma_f32 v[160:161], v[150:151], v[118:119], v[160:161]
	v_pk_fma_f32 v[162:163], v[150:151], v[126:127], v[162:163]
	v_pk_fma_f32 v[164:165], v[150:151], v[134:135], v[164:165]
	v_pk_fma_f32 v[156:157], v[152:153], v[104:105], v[156:157]
	v_pk_fma_f32 v[158:159], v[152:153], v[112:113], v[158:159]
	v_pk_fma_f32 v[160:161], v[152:153], v[120:121], v[160:161]
	v_pk_fma_f32 v[162:163], v[152:153], v[128:129], v[162:163]
	v_pk_fma_f32 v[164:165], v[152:153], v[136:137], v[164:165]
	v_pk_fma_f32 v[156:157], v[154:155], v[106:107], v[156:157]
	v_pk_fma_f32 v[158:159], v[154:155], v[114:115], v[158:159]
	v_pk_fma_f32 v[160:161], v[154:155], v[122:123], v[160:161]
	v_pk_fma_f32 v[162:163], v[154:155], v[130:131], v[162:163]
	v_pk_fma_f32 v[164:165], v[154:155], v[138:139], v[164:165]
	ds_read_b128 v[100:103], v26 offset:800
	ds_read_b128 v[104:107], v26 offset:816
	ds_read_b128 v[108:111], v26 offset:832
	ds_read_b128 v[112:115], v26 offset:848
	ds_read_b128 v[116:119], v26 offset:864
	ds_read_b128 v[120:123], v26 offset:880
	ds_read_b128 v[124:127], v26 offset:896
	ds_read_b128 v[128:131], v26 offset:912
	ds_read_b128 v[132:135], v26 offset:928
	ds_read_b128 v[136:139], v26 offset:944
	s_waitcnt vmcnt(7)
; __device__ __forceinline__ void cb_item(const bf16_t* WT, int ldw, int K, int n0, const float* shift, float* out, int ostride, int lane) {
;     ...
;     for (int k8 = 0; k8 < K; k8 += 8) {
;         const u32x4 q = *(const u32x4*)(wp + k8);
;         float w[8];
; #pragma unroll
;         for (int e = 0; e < 4; ++e) { w[2 * e] = __uint_as_float(q[e] << 16); w[2 * e + 1] = __uint_as_float(q[e] & 0xffff0000u); }
; #pragma unroll
;         for (int b = 0; b < 5; ++b) { const float* sp = shift + (size_t)b * 9216 + k8;
; #pragma unroll
;             for (int e = 0; e < 8; ++e) a[b] += w[e] * sp[e]; }
	v_lshlrev_b32_e32 v148, 16, v44
	v_and_b32_e32 v149, 0xffff0000, v44
	v_lshlrev_b32_e32 v150, 16, v45
	v_and_b32_e32 v151, 0xffff0000, v45
	v_lshlrev_b32_e32 v152, 16, v46
	v_and_b32_e32 v153, 0xffff0000, v46
	v_lshlrev_b32_e32 v154, 16, v47
	v_and_b32_e32 v155, 0xffff0000, v47
	global_load_dwordx4 v[44:47], v25, s[32:33] offset:192
	s_waitcnt lgkmcnt(10)
	v_pk_fma_f32 v[156:157], v[148:149], v[60:61], v[156:157]
	v_pk_fma_f32 v[158:159], v[148:149], v[68:69], v[158:159]
	v_pk_fma_f32 v[160:161], v[148:149], v[76:77], v[160:161]
	v_pk_fma_f32 v[162:163], v[148:149], v[84:85], v[162:163]
	v_pk_fma_f32 v[164:165], v[148:149], v[92:93], v[164:165]
	v_pk_fma_f32 v[156:157], v[150:151], v[62:63], v[156:157]
	v_pk_fma_f32 v[158:159], v[150:151], v[70:71], v[158:159]
	v_pk_fma_f32 v[160:161], v[150:151], v[78:79], v[160:161]
	v_pk_fma_f32 v[162:163], v[150:151], v[86:87], v[162:163]
	v_pk_fma_f32 v[164:165], v[150:151], v[94:95], v[164:165]
	v_pk_fma_f32 v[156:157], v[152:153], v[64:65], v[156:157]
	v_pk_fma_f32 v[158:159], v[152:153], v[72:73], v[158:159]
	v_pk_fma_f32 v[160:161], v[152:153], v[80:81], v[160:161]
	v_pk_fma_f32 v[162:163], v[152:153], v[88:89], v[162:163]
	v_pk_fma_f32 v[164:165], v[152:153], v[96:97], v[164:165]
	v_pk_fma_f32 v[156:157], v[154:155], v[66:67], v[156:157]
	v_pk_fma_f32 v[158:159], v[154:155], v[74:75], v[158:159]
	v_pk_fma_f32 v[160:161], v[154:155], v[82:83], v[160:161]
	v_pk_fma_f32 v[162:163], v[154:155], v[90:91], v[162:163]
	v_pk_fma_f32 v[164:165], v[154:155], v[98:99], v[164:165]
	ds_read_b128 v[60:63], v26 offset:960
	ds_read_b128 v[64:67], v26 offset:976
	ds_read_b128 v[68:71], v26 offset:992
	ds_read_b128 v[72:75], v26 offset:1008
	ds_read_b128 v[76:79], v26 offset:1024
	ds_read_b128 v[80:83], v26 offset:1040
	ds_read_b128 v[84:87], v26 offset:1056
	ds_read_b128 v[88:91], v26 offset:1072
	ds_read_b128 v[92:95], v26 offset:1088
	ds_read_b128 v[96:99], v26 offset:1104
	s_waitcnt vmcnt(7)
	v_lshlrev_b32_e32 v148, 16, v48
	v_and_b32_e32 v149, 0xffff0000, v48
	v_lshlrev_b32_e32 v150, 16, v49
	v_and_b32_e32 v151, 0xffff0000, v49
	v_lshlrev_b32_e32 v152, 16, v50
	v_and_b32_e32 v153, 0xffff0000, v50
	v_lshlrev_b32_e32 v154, 16, v51
	v_and_b32_e32 v155, 0xffff0000, v51
	global_load_dwordx4 v[48:51], v25, s[32:33] offset:208
	s_waitcnt lgkmcnt(10)
	v_pk_fma_f32 v[156:157], v[148:149], v[100:101], v[156:157]
	v_pk_fma_f32 v[158:159], v[148:149], v[108:109], v[158:159]
	v_pk_fma_f32 v[160:161], v[148:149], v[116:117], v[160:161]
	v_pk_fma_f32 v[162:163], v[148:149], v[124:125], v[162:163]
	v_pk_fma_f32 v[164:165], v[148:149], v[132:133], v[164:165]
	v_pk_fma_f32 v[156:157], v[150:151], v[102:103], v[156:157]
	v_pk_fma_f32 v[158:159], v[150:151], v[110:111], v[158:159]
	v_pk_fma_f32 v[160:161], v[150:151], v[118:119], v[160:161]
	v_pk_fma_f32 v[162:163], v[150:151], v[126:127], v[162:163]
	v_pk_fma_f32 v[164:165], v[150:151], v[134:135], v[164:165]
	v_pk_fma_f32 v[156:157], v[152:153], v[104:105], v[156:157]
	v_pk_fma_f32 v[158:159], v[152:153], v[112:113], v[158:159]
	v_pk_fma_f32 v[160:161], v[152:153], v[120:121], v[160:161]
	v_pk_fma_f32 v[162:163], v[152:153], v[128:129], v[162:163]
	v_pk_fma_f32 v[164:165], v[152:153], v[136:137], v[164:165]
	v_pk_fma_f32 v[156:157], v[154:155], v[106:107], v[156:157]
	v_pk_fma_f32 v[158:159], v[154:155], v[114:115], v[158:159]
	v_pk_fma_f32 v[160:161], v[154:155], v[122:123], v[160:161]
	v_pk_fma_f32 v[162:163], v[154:155], v[130:131], v[162:163]
	v_pk_fma_f32 v[164:165], v[154:155], v[138:139], v[164:165]
	ds_read_b128 v[100:103], v26 offset:1120
	ds_read_b128 v[104:107], v26 offset:1136
	ds_read_b128 v[108:111], v26 offset:1152
	ds_read_b128 v[112:115], v26 offset:1168
	ds_read_b128 v[116:119], v26 offset:1184
	ds_read_b128 v[120:123], v26 offset:1200
	ds_read_b128 v[124:127], v26 offset:1216
	ds_read_b128 v[128:131], v26 offset:1232
	ds_read_b128 v[132:135], v26 offset:1248
	ds_read_b128 v[136:139], v26 offset:1264
	s_waitcnt vmcnt(7)
	v_lshlrev_b32_e32 v148, 16, v52
	v_and_b32_e32 v149, 0xffff0000, v52
	v_lshlrev_b32_e32 v150, 16, v53
	v_and_b32_e32 v151, 0xffff0000, v53
	v_lshlrev_b32_e32 v152, 16, v54
	v_and_b32_e32 v153, 0xffff0000, v54
	v_lshlrev_b32_e32 v154, 16, v55
	v_and_b32_e32 v155, 0xffff0000, v55
	global_load_dwordx4 v[52:55], v25, s[32:33] offset:224
	s_waitcnt lgkmcnt(10)
; __device__ __forceinline__ void cb_item(const bf16_t* WT, int ldw, int K, int n0, const float* shift, float* out, int ostride, int lane) {
;     ...
;     for (int k8 = 0; k8 < K; k8 += 8) {
;         const u32x4 q = *(const u32x4*)(wp + k8);
;         float w[8];
; #pragma unroll
;         for (int e = 0; e < 4; ++e) { w[2 * e] = __uint_as_float(q[e] << 16); w[2 * e + 1] = __uint_as_float(q[e] & 0xffff0000u); }
; #pragma unroll
;         for (int b = 0; b < 5; ++b) { const float* sp = shift + (size_t)b * 9216 + k8;
; #pragma unroll
;             for (int e = 0; e < 8; ++e) a[b] += w[e] * sp[e]; }
;     }
; #pragma unroll
;     for (int b = 0; b < 5; ++b) out[(size_t)b * ostride + n0 + lane] = a[b];
	v_pk_fma_f32 v[156:157], v[148:149], v[60:61], v[156:157]
	v_pk_fma_f32 v[158:159], v[148:149], v[68:69], v[158:159]
	v_pk_fma_f32 v[160:161], v[148:149], v[76:77], v[160:161]
	v_pk_fma_f32 v[162:163], v[148:149], v[84:85], v[162:163]
	v_pk_fma_f32 v[164:165], v[148:149], v[92:93], v[164:165]
	v_pk_fma_f32 v[156:157], v[150:151], v[62:63], v[156:157]
	v_pk_fma_f32 v[158:159], v[150:151], v[70:71], v[158:159]
	v_pk_fma_f32 v[160:161], v[150:151], v[78:79], v[160:161]
	v_pk_fma_f32 v[162:163], v[150:151], v[86:87], v[162:163]
	v_pk_fma_f32 v[164:165], v[150:151], v[94:95], v[164:165]
	v_pk_fma_f32 v[156:157], v[152:153], v[64:65], v[156:157]
	v_pk_fma_f32 v[158:159], v[152:153], v[72:73], v[158:159]
	v_pk_fma_f32 v[160:161], v[152:153], v[80:81], v[160:161]
	v_pk_fma_f32 v[162:163], v[152:153], v[88:89], v[162:163]
	v_pk_fma_f32 v[164:165], v[152:153], v[96:97], v[164:165]
	v_pk_fma_f32 v[156:157], v[154:155], v[66:67], v[156:157]
	v_pk_fma_f32 v[158:159], v[154:155], v[74:75], v[158:159]
	v_pk_fma_f32 v[160:161], v[154:155], v[82:83], v[160:161]
	v_pk_fma_f32 v[162:163], v[154:155], v[90:91], v[162:163]
	v_pk_fma_f32 v[164:165], v[154:155], v[98:99], v[164:165]
	ds_read_b128 v[60:63], v26 offset:1280
	ds_read_b128 v[64:67], v26 offset:1296
	ds_read_b128 v[68:71], v26 offset:1312
	ds_read_b128 v[72:75], v26 offset:1328
	ds_read_b128 v[76:79], v26 offset:1344
	ds_read_b128 v[80:83], v26 offset:1360
	ds_read_b128 v[84:87], v26 offset:1376
	ds_read_b128 v[88:91], v26 offset:1392
	ds_read_b128 v[92:95], v26 offset:1408
	ds_read_b128 v[96:99], v26 offset:1424
	s_waitcnt vmcnt(7)
	v_lshlrev_b32_e32 v148, 16, v56
	v_and_b32_e32 v149, 0xffff0000, v56
	v_lshlrev_b32_e32 v150, 16, v57
	v_and_b32_e32 v151, 0xffff0000, v57
	v_lshlrev_b32_e32 v152, 16, v58
	v_and_b32_e32 v153, 0xffff0000, v58
	v_lshlrev_b32_e32 v154, 16, v59
	v_and_b32_e32 v155, 0xffff0000, v59
	global_load_dwordx4 v[56:59], v25, s[32:33] offset:240
	s_waitcnt lgkmcnt(10)
	v_pk_fma_f32 v[156:157], v[148:149], v[100:101], v[156:157]
	v_pk_fma_f32 v[158:159], v[148:149], v[108:109], v[158:159]
	v_pk_fma_f32 v[160:161], v[148:149], v[116:117], v[160:161]
	v_pk_fma_f32 v[162:163], v[148:149], v[124:125], v[162:163]
	v_pk_fma_f32 v[164:165], v[148:149], v[132:133], v[164:165]
	v_pk_fma_f32 v[156:157], v[150:151], v[102:103], v[156:157]
	v_pk_fma_f32 v[158:159], v[150:151], v[110:111], v[158:159]
	v_pk_fma_f32 v[160:161], v[150:151], v[118:119], v[160:161]
	v_pk_fma_f32 v[162:163], v[150:151], v[126:127], v[162:163]
	v_pk_fma_f32 v[164:165], v[150:151], v[134:135], v[164:165]
	v_pk_fma_f32 v[156:157], v[152:153], v[104:105], v[156:157]
	v_pk_fma_f32 v[158:159], v[152:153], v[112:113], v[158:159]
	v_pk_fma_f32 v[160:161], v[152:153], v[120:121], v[160:161]
	v_pk_fma_f32 v[162:163], v[152:153], v[128:129], v[162:163]
	v_pk_fma_f32 v[164:165], v[152:153], v[136:137], v[164:165]
	v_pk_fma_f32 v[156:157], v[154:155], v[106:107], v[156:157]
	v_pk_fma_f32 v[158:159], v[154:155], v[114:115], v[158:159]
	v_pk_fma_f32 v[160:161], v[154:155], v[122:123], v[160:161]
	v_pk_fma_f32 v[162:163], v[154:155], v[130:131], v[162:163]
	v_pk_fma_f32 v[164:165], v[154:155], v[138:139], v[164:165]
	v_add_u32_e32 v25, 0x80, v25
	v_add_u32_e32 v26, 0x500, v26
	s_add_i32 s100, s100, -1
	s_cmp_lg_u32 s100, 0
	s_cbranch_scc1 .Lcb_loop_b_1
	s_waitcnt vmcnt(0) lgkmcnt(0)
	s_lshl_b32 s0, s37, 8
	s_add_u32 s0, s0, 0x152800
	s_add_u32 s0, s76, s0
	s_addc_u32 s1, s77, 0
	v_lshlrev_b32_e32 v27, 2, v16
	v_add_f32_e32 v20, v156, v157
	v_add_f32_e32 v21, v158, v159
	v_add_f32_e32 v22, v160, v161
	v_add_f32_e32 v23, v162, v163
	v_add_f32_e32 v24, v164, v165
	global_store_dword v27, v20, s[0:1]
	s_add_u32 s0, s0, 0x5800
	s_addc_u32 s1, s1, 0
	global_store_dword v27, v21, s[0:1]
	s_add_u32 s0, s0, 0x5800
	s_addc_u32 s1, s1, 0
	global_store_dword v27, v22, s[0:1]
	s_add_u32 s0, s0, 0x5800
	s_addc_u32 s1, s1, 0
	global_store_dword v27, v23, s[0:1]
	s_add_u32 s0, s0, 0x5800
	s_addc_u32 s1, s1, 0
	global_store_dword v27, v24, s[0:1]
	s_branch .Ltr_fin_b
